# phase 6: attention setup loads issued before the scan staging wait
# baseline (speedup 1.0000x reference)
; __device__ __forceinline__ void attn_unit(int b, int qb, int kvh, const bf16_t* __restrict__ QP, const bf16_t* __restrict__ KP, const bf16_t* __restrict__ VT, const float* sink, bf16_t* MIX, unsigned char* ldsb, int tid, int wave, int lane) {
;     const int fr = lane & 15, fq = lane >> 4, hq = kvh * 4 + (wave >> 1), q0 = qb * 64 + (wave & 1) * 32;
;     bf16x8 qf[2][2];
; #pragma unroll
;     for (int qt = 0; qt < 2; ++qt)
; #pragma unroll
;         for (int ks = 0; ks < 2; ++ks) qf[qt][ks] = *(const bf16x8*)(QP + ((size_t)(b * 4096 + q0 + qt * 16 + fr) * 8 + hq) * 64 + ks * 32 + fq * 8);
;     const bf16_t* Kb = KP + (size_t)(b * 2 + kvh) * KPL * 64; const bf16_t* Vb = VT + (size_t)(b * 2 + kvh) * 64 * KPL;
;     float mrun[2], lrun[2]; f32x4 o[4][2];
;     const float sk = sink[hq] * LOG2E;
; #pragma unroll
;     for (int qt = 0; qt < 2; ++qt) { mrun[qt] = sk; lrun[qt] = fq == 0 ? 1.0f : 0.0f;
; #pragma unroll
;         for (int dt = 0; dt < 4; ++dt) o[dt][qt] = (f32x4){0.f, 0.f, 0.f, 0.f}; }
;     const int first = qb == 0 ? 2 : (qb == 1 ? 1 : 0), lastw = (65 - qb) < 4 ? (65 - qb) : 4, nW = lastw - first + 1, nT = nW + 4;
;     ...
;     bf16_t* const lb = (bf16_t*)ldsb; const int lr = tid >> 3, lc = tid & 7;
;     u32x4 kreg = *(const u32x4*)(Kb + (size_t)(ATT_KS0(0) + lr) * 64 + lc * 8), vreg = *(const u32x4*)(Vb + (size_t)lr * KPL + ATT_KS0(0) + lc * 8);
; __device__ __forceinline__ void scan_phase(const Ctx& X, const float* S, const float* AT, bf16_t* A2) {
;     if (X.tid >= 128) return;
;     const int id = X.bx * 128 + X.tid; if (id >= 8 * 32 * 128) return;
;     const int p = id & 63, dir = (id >> 6) & 1, g = (id >> 7) & 31, b = id >> 12;
;     const float ar = AT[((g * 2 + dir) * 64 + p) * 2], ai = AT[((g * 2 + dir) * 64 + p) * 2 + 1];
;     const float* Sg = S + (size_t)g * A2ROWS * 256 + dir * 128 + p; bf16_t* Hg = A2 + (size_t)g * A2ROWS * A2K + 512 + dir * 128 + p;
.Lat_sdma_nx:
	s_add_u32 s33, s33, 8
	s_cmp_lt_u32 s33, 0x88
	s_cbranch_scc1 .Lat_sdma
	v_readlane_b32 s46, v254, 4
	v_readlane_b32 s47, v254, 5
	s_and_b32 s44, s2, 31
	s_lshl_b32 s44, s44, 1
	s_and_b32 s7, s12, 1
	s_add_u32 s44, s44, s7
	s_lshl_b32 s44, s44, 9
	s_add_u32 s46, s46, s44
	s_addc_u32 s47, s47, 0
	v_lshlrev_b32_e32 v84, 3, v1
	global_load_dwordx2 v[92:93], v84, s[46:47]
	s_lshr_b32 s13, s2, 1
	s_and_b32 s13, s13, 63
	s_and_b32 s0, s2, 1
	s_lshr_b32 s1, s2, 7
	s_sub_u32 s21, 2, s13
	s_max_i32 s21, s21, 0
	s_sub_u32 s4, 0x41, s13
	s_min_i32 s4, s4, 4
	s_sub_u32 s24, s4, s21
	s_add_u32 s24, s24, 1
	s_add_u32 s25, s24, 4
	s_lshl_b32 s26, s25, 2
	s_lshl_b32 s34, s12, 10
	s_lshl_b32 s4, s1, 1
	s_add_u32 s4, s4, s0
	s_mul_i32 s4, s4, 0x88000
	s_add_u32 s8, s88, s4
	s_addc_u32 s9, s89, 0
	s_add_u32 s10, s8, 0x17d00000
	s_addc_u32 s11, s9, 0
	s_add_u32 s8, s8, 0x17400000
	s_addc_u32 s9, s9, 0
	s_lshr_b32 s4, s12, 1
	s_lshl_b32 s5, s0, 2
	s_add_u32 s4, s4, s5
	s_lshl_b32 s5, s1, 12
	s_lshl_b32 s6, s13, 6
	s_add_u32 s5, s5, s6
	s_and_b32 s6, s12, 1
	s_lshl_b32 s7, s6, 5
	s_add_u32 s5, s5, s7
	s_lshl_b32 s7, s4, 7
	s_lshl_b32 s44, s5, 10
	s_add_u32 s44, s44, s7
	s_add_u32 s50, s88, s44
	s_addc_u32 s51, s89, 0
	s_add_u32 s50, s50, 0x10d00000
	s_addc_u32 s51, s51, 0
	s_lshl_b32 s44, s5, 11
	s_add_u32 s44, s44, s7
	s_add_u32 s52, s88, s44
	s_addc_u32 s53, s89, 0
	s_add_u32 s52, s52, 0x1a600000
	s_addc_u32 s53, s53, 0
	s_lshl_b32 s44, s4, 2
	s_load_dword s45, s[62:63], s44
	v_and_b32_e32 v80, 15, v1
	v_lshrrev_b32_e32 v81, 4, v1
	v_lshrrev_b32_e32 v82, 1, v80
	v_lshlrev_b32_e32 v83, 7, v80
	v_xor_b32_e32 v84, v81, v82
	v_lshl_add_u32 v2, v84, 4, v83
	v_xor_b32_e32 v3, 64, v2
	v_lshrrev_b32_e32 v84, 1, v81
	v_xor_b32_e32 v84, v84, v82
	v_lshl_add_u32 v84, v84, 4, v83
	v_and_b32_e32 v85, 1, v81
	v_lshl_add_u32 v4, v85, 3, v84
	v_xor_b32_e32 v5, 32, v4
	v_xor_b32_e32 v6, 64, v4
	v_xor_b32_e32 v7, 0x60, v4
	v_lshrrev_b32_e32 v84, 3, v1
	v_and_b32_e32 v85, 7, v1
	v_lshrrev_b32_e32 v86, 1, v84
	s_lshl_b32 s44, s6, 2
	v_or_b32_e32 v86, s44, v86
	v_xor_b32_e32 v85, v85, v86
	v_lshlrev_b32_e32 v85, 4, v85
	s_lshl_b32 s44, s12, 3
	v_add_u32_e32 v84, s44, v84
	v_lshl_add_u32 v14, v84, 7, v85
	s_movk_i32 s44, 0x2200
	v_mul_lo_u32 v86, v84, s44
	v_add_u32_e32 v15, v86, v85
	v_lshlrev_b32_e32 v84, 10, v80
	v_lshl_add_u32 v248, v81, 4, v84
	v_add_u32_e32 v249, 0x4000, v248
	v_lshlrev_b32_e32 v84, 11, v80
	v_lshl_add_u32 v200, v81, 3, v84
	v_add_u32_e32 v201, 0x8000, v200
	global_load_dwordx4 v[16:19], v248, s[50:51]
	global_load_dwordx4 v[20:23], v248, s[50:51] offset:64
	global_load_dwordx4 v[24:27], v249, s[50:51]
	global_load_dwordx4 v[28:31], v249, s[50:51] offset:64
	v_readlane_b32 s46, v254, 0
	v_readlane_b32 s47, v254, 1
	s_sub_u32 s46, s46, 0xd8
	s_subb_u32 s47, s47, 0
	s_load_dwordx2 s[40:41], s[46:47], 0x58
	s_load_dwordx2 s[42:43], s[46:47], 0x60
	v_lshlrev_b32_e32 v84, 2, v1
	s_waitcnt lgkmcnt(0)
	global_load_dword v85, v84, s[40:41]
	global_load_dword v86, v84, s[42:43]
	s_waitcnt vmcnt(0) lgkmcnt(0)
	s_barrier
	s_cmp_lt_u32 s12, 2
	s_cbranch_scc0 .Lat_scan_done
	s_and_b32 s0, s2, 31
	s_lshr_b32 s1, s2, 5
	s_mul_i32 s4, s0, 0x1e0000
	s_add_u32 s40, s88, s4
	s_addc_u32 s41, s89, 0
	s_lshl_b32 s4, s1, 7
	s_mul_i32 s5, s12, 0x7f
	s_add_u32 s4, s4, s5
	s_mul_i32 s4, s4, 0x600
	s_lshl_b32 s5, s12, 8
	s_add_u32 s4, s4, s5
	s_add_u32 s4, s4, 0xa900400
	s_add_u32 s40, s40, s4
	s_addc_u32 s41, s41, 0
	s_mov_b32 s42, 0x600
	s_mov_b32 s43, 0
	s_cmp_eq_u32 s12, 0
	s_cbranch_scc1 .Lat_scan_fwd
	s_mov_b32 s42, 0xfffffa00
	s_mov_b32 s43, -1

; __device__ __forceinline__ void attn_unit(int b, int qb, int kvh, const bf16_t* __restrict__ QP, const bf16_t* __restrict__ KP, const bf16_t* __restrict__ VT, const float* sink, bf16_t* MIX, unsigned char* ldsb, int tid, int wave, int lane) {
;     ...
;     float mrun[2], lrun[2]; f32x4 o[4][2];
;     const float sk = sink[hq] * LOG2E;
; #pragma unroll
;     for (int qt = 0; qt < 2; ++qt) { mrun[qt] = sk; lrun[qt] = fq == 0 ? 1.0f : 0.0f;
; #pragma unroll
;         for (int dt = 0; dt < 4; ++dt) o[dt][qt] = (f32x4){0.f, 0.f, 0.f, 0.f}; }
;     const int first = qb == 0 ? 2 : (qb == 1 ? 1 : 0), lastw = (65 - qb) < 4 ? (65 - qb) : 4, nW = lastw - first + 1, nT = nW + 4;
;     ...
;     bf16_t* const lb = (bf16_t*)ldsb; const int lr = tid >> 3, lc = tid & 7;
;     u32x4 kreg = *(const u32x4*)(Kb + (size_t)(ATT_KS0(0) + lr) * 64 + lc * 8), vreg = *(const u32x4*)(Vb + (size_t)lr * KPL + ATT_KS0(0) + lc * 8);
;     __syncthreads();
;     *(u32x4*)(lb + lr * 72 + lc * 8) = kreg; *(u32x4*)(lb + 4608 + lr * 72 + lc * 8) = vreg;
;     __syncthreads();
;     for (int jt = 0; jt < nT; ++jt) {
;         const int ks0 = ATT_KS0(jt); const bool needmask = (jt < nW) && !((ks0 + 63 - q0 <= 128) && (q0 + 31 - ks0 <= 128)); const bf16_t* Kc = lb + (jt & 1) * 9216; const bf16_t* Vc = Kc + 4608;
;     ...
;                 for (int j = 0; j < 4; ++j) { float v = s[kt][qt][j]; if (needmask) { const int dd = ks0 + kt * 16 + 4 * fq + j - qpos; if (dd > 128 || dd < -128) v = -1.0e30f; s[kt][qt][j] = v; } mx = fmaxf(mx, v); }
.Lat_scan_done:
	s_barrier
	v_max_f32_e64 v85, |v85|, |v85|
	v_max_f32_e64 v86, |v86|, |v86|
	s_nop 1
	v_max_f32_dpp v85, v85, v85 quad_perm:[1,0,3,2] row_mask:0xf bank_mask:0xf
	s_nop 1
	v_max_f32_dpp v85, v85, v85 quad_perm:[2,3,0,1] row_mask:0xf bank_mask:0xf
	s_nop 1
	v_max_f32_dpp v85, v85, v85 row_half_mirror row_mask:0xf bank_mask:0xf
	s_nop 1
	v_max_f32_dpp v85, v85, v85 row_mirror row_mask:0xf bank_mask:0xf
	s_nop 1
	v_mov_b32_e32 v87, v85
	s_nop 1
	v_permlane16_swap_b32_e32 v85, v87
	s_nop 0
	v_max_f32_e32 v85, v85, v87
	v_mov_b32_e32 v87, v85
	s_nop 1
	v_permlane32_swap_b32_e32 v85, v87
	s_nop 0
	v_max_f32_e32 v85, v85, v87
	s_nop 1
	v_max_f32_dpp v86, v86, v86 quad_perm:[1,0,3,2] row_mask:0xf bank_mask:0xf
	s_nop 1
	v_max_f32_dpp v86, v86, v86 quad_perm:[2,3,0,1] row_mask:0xf bank_mask:0xf
	s_nop 1
	v_max_f32_dpp v86, v86, v86 row_half_mirror row_mask:0xf bank_mask:0xf
	s_nop 1
	v_max_f32_dpp v86, v86, v86 row_mirror row_mask:0xf bank_mask:0xf
	s_nop 1
	v_mov_b32_e32 v87, v86
	s_nop 1
	v_permlane16_swap_b32_e32 v86, v87
	s_nop 0
	v_max_f32_e32 v86, v86, v87
	v_mov_b32_e32 v87, v86
	s_nop 1
	v_permlane32_swap_b32_e32 v86, v87
	s_nop 0
	v_max_f32_e32 v86, v86, v87
	v_mul_f32_e32 v85, v85, v86
	v_mov_b32_e32 v86, 0.5
	v_fmamk_f32 v85, v85, 0x413c5bb7, v86
	v_mov_b32_e32 v86, 0x3fb8aa3b
	v_mul_f32_e32 v86, s45, v86
	v_max_f32_e32 v85, v85, v86
	v_sub_f32_e32 v251, 0, v85
	v_sub_f32_e32 v86, v86, v85
	v_exp_f32_e32 v86, v86
	v_mov_b32_e32 v253, 0
	v_mov_b32_e32 v252, 0xf149f2ca
	v_cmp_gt_u32_e64 s[4:5], 16, v1
	s_nop 1
	v_cndmask_b32_e64 v250, 0, v86, s[4:5]
	v_mov_b32_e32 v196, v251
	v_mov_b32_e32 v197, v251
	v_mov_b32_e32 v198, v251
	v_mov_b32_e32 v199, v251
	v_lshlrev_b32_e32 v84, 2, v81
	v_sub_u32_e32 v84, v84, v80
	s_and_b32 s44, s12, 1
	s_lshl_b32 s44, s44, 5
	v_subrev_u32_e32 v84, s44, v84
	v_add_u32_e32 v85, -16, v84
	v_cmp_le_i32_e64 s[4:5], 0, v85
	v_cmp_ge_i32_e64 s[6:7], 0, v85
	s_nop 1
	v_cndmask_b32_e64 v208, v252, v251, s[4:5]
	v_cndmask_b32_e64 v228, v252, v251, s[6:7]
	v_add_u32_e32 v85, -15, v84
	v_cmp_le_i32_e64 s[4:5], 0, v85
	v_cmp_ge_i32_e64 s[6:7], 0, v85
	s_nop 1
	v_cndmask_b32_e64 v209, v252, v251, s[4:5]
	v_cndmask_b32_e64 v229, v252, v251, s[6:7]
	v_add_u32_e32 v85, -14, v84
	v_cmp_le_i32_e64 s[4:5], 0, v85
	v_cmp_ge_i32_e64 s[6:7], 0, v85
	s_nop 1
	v_cndmask_b32_e64 v210, v252, v251, s[4:5]
	v_cndmask_b32_e64 v230, v252, v251, s[6:7]
	v_add_u32_e32 v85, -13, v84
	v_cmp_le_i32_e64 s[4:5], 0, v85
	v_cmp_ge_i32_e64 s[6:7], 0, v85
	s_nop 1
	v_cndmask_b32_e64 v211, v252, v251, s[4:5]
	v_cndmask_b32_e64 v231, v252, v251, s[6:7]
	v_add_u32_e32 v85, 0, v84
	v_cmp_le_i32_e64 s[4:5], 0, v85
	v_cmp_ge_i32_e64 s[6:7], 0, v85
	s_nop 1
	v_cndmask_b32_e64 v212, v252, v251, s[4:5]
	v_cndmask_b32_e64 v232, v252, v251, s[6:7]
	v_add_u32_e32 v85, 1, v84
	v_cmp_le_i32_e64 s[4:5], 0, v85
	v_cmp_ge_i32_e64 s[6:7], 0, v85
	s_nop 1
	v_cndmask_b32_e64 v213, v252, v251, s[4:5]
	v_cndmask_b32_e64 v233, v252, v251, s[6:7]
	v_add_u32_e32 v85, 2, v84
	v_cmp_le_i32_e64 s[4:5], 0, v85
	v_cmp_ge_i32_e64 s[6:7], 0, v85
	s_nop 1
	v_cndmask_b32_e64 v214, v252, v251, s[4:5]
	v_cndmask_b32_e64 v234, v252, v251, s[6:7]
	v_add_u32_e32 v85, 3, v84
	v_cmp_le_i32_e64 s[4:5], 0, v85
	v_cmp_ge_i32_e64 s[6:7], 0, v85
	s_nop 1
	v_cndmask_b32_e64 v215, v252, v251, s[4:5]
	v_cndmask_b32_e64 v235, v252, v251, s[6:7]
	v_add_u32_e32 v85, 16, v84
	v_cmp_le_i32_e64 s[4:5], 0, v85
	v_cmp_ge_i32_e64 s[6:7], 0, v85
	s_nop 1
	v_cndmask_b32_e64 v216, v252, v251, s[4:5]
	v_cndmask_b32_e64 v236, v252, v251, s[6:7]
	v_add_u32_e32 v85, 17, v84
	v_cmp_le_i32_e64 s[4:5], 0, v85
	v_cmp_ge_i32_e64 s[6:7], 0, v85
	s_nop 1
	v_cndmask_b32_e64 v217, v252, v251, s[4:5]
	v_cndmask_b32_e64 v237, v252, v251, s[6:7]
	v_add_u32_e32 v85, 18, v84
	v_cmp_le_i32_e64 s[4:5], 0, v85
	v_cmp_ge_i32_e64 s[6:7], 0, v85
	s_nop 1
	v_cndmask_b32_e64 v218, v252, v251, s[4:5]
	v_cndmask_b32_e64 v238, v252, v251, s[6:7]
	v_add_u32_e32 v85, 19, v84
	v_cmp_le_i32_e64 s[4:5], 0, v85
	v_cmp_ge_i32_e64 s[6:7], 0, v85
	s_nop 1
	v_cndmask_b32_e64 v219, v252, v251, s[4:5]
	v_cndmask_b32_e64 v239, v252, v251, s[6:7]
	v_add_u32_e32 v85, 32, v84
	v_cmp_le_i32_e64 s[4:5], 0, v85
	v_cmp_ge_i32_e64 s[6:7], 0, v85
	s_nop 1
	v_cndmask_b32_e64 v220, v252, v251, s[4:5]
	v_cndmask_b32_e64 v240, v252, v251, s[6:7]
	v_add_u32_e32 v85, 33, v84
	v_cmp_le_i32_e64 s[4:5], 0, v85
	v_cmp_ge_i32_e64 s[6:7], 0, v85
	s_nop 1
	v_cndmask_b32_e64 v221, v252, v251, s[4:5]
	v_cndmask_b32_e64 v241, v252, v251, s[6:7]
	v_add_u32_e32 v85, 34, v84
	v_cmp_le_i32_e64 s[4:5], 0, v85
	v_cmp_ge_i32_e64 s[6:7], 0, v85
	s_nop 1
	v_cndmask_b32_e64 v222, v252, v251, s[4:5]
	v_cndmask_b32_e64 v242, v252, v251, s[6:7]
	v_add_u32_e32 v85, 35, v84
	v_cmp_le_i32_e64 s[4:5], 0, v85
	v_cmp_ge_i32_e64 s[6:7], 0, v85
	s_nop 1
	v_cndmask_b32_e64 v223, v252, v251, s[4:5]
	v_cndmask_b32_e64 v243, v252, v251, s[6:7]
	v_add_u32_e32 v85, 48, v84
	v_cmp_le_i32_e64 s[4:5], 0, v85
	v_cmp_ge_i32_e64 s[6:7], 0, v85
	s_nop 1
	v_cndmask_b32_e64 v224, v252, v251, s[4:5]
	v_cndmask_b32_e64 v244, v252, v251, s[6:7]
	v_add_u32_e32 v85, 49, v84
	v_cmp_le_i32_e64 s[4:5], 0, v85
	v_cmp_ge_i32_e64 s[6:7], 0, v85
	s_nop 1
	v_cndmask_b32_e64 v225, v252, v251, s[4:5]
	v_cndmask_b32_e64 v245, v252, v251, s[6:7]
	v_add_u32_e32 v85, 50, v84
	v_cmp_le_i32_e64 s[4:5], 0, v85
	v_cmp_ge_i32_e64 s[6:7], 0, v85
	s_nop 1
	v_cndmask_b32_e64 v226, v252, v251, s[4:5]
	v_cndmask_b32_e64 v246, v252, v251, s[6:7]
	v_add_u32_e32 v85, 51, v84
	v_cmp_le_i32_e64 s[4:5], 0, v85
	v_cmp_ge_i32_e64 s[6:7], 0, v85
	s_nop 1
	v_cndmask_b32_e64 v227, v252, v251, s[4:5]
	v_cndmask_b32_e64 v247, v252, v251, s[6:7]
	s_mov_b32 s27, 0
	s_mov_b32 s30, 0
	s_mov_b32 s31, 0
	s_mov_b32 s28, 0
	s_mov_b32 s29, 0
	s_mov_b32 s35, 0
	s_cmp_lt_u32 s28, s24
	s_cbranch_scc0 .Lat_ctx_1
	s_add_u32 s44, s13, s21
	s_add_u32 s44, s44, s28
	s_lshl_b32 s44, s44, 6
	s_sub_u32 s44, s44, 0x80
	s_branch .Lat_ks_2
